# GEMM K-loops: removed the back-to-back s_setprio 0 / s_setprio 1 pair in the middle of each 32-MFMA block (12 sites)
# speedup vs baseline: 1.0056x; 1.0021x over previous
.LBB0_50:
	s_add_u32 s8, s58, 0xfffc0080
	s_addc_u32 s9, s59, -1
	s_add_i32 s10, 0, 0x10000
	s_cmp_eq_u32 s85, 12
	s_cselect_b32 s41, s53, s9
	s_cselect_b32 s40, s69, s8
	s_cselect_b32 s29, s51, s84
	s_cselect_b32 s28, s72, s73
	s_add_i32 s11, 0, 0x14000
	v_add_u32_e32 v158, s10, v150
	v_add_u32_e32 v174, s11, v150
	ds_read_b128 v[142:145], v158
	ds_read_b128 v[146:149], v158 offset:1024
	ds_read_b128 v[154:157], v158 offset:2048
	ds_read_b128 v[158:161], v158 offset:3072
	ds_read_b128 v[162:165], v174
	ds_read_b128 v[166:169], v174 offset:1024
	ds_read_b128 v[170:173], v174 offset:2048
	ds_read_b128 v[174:177], v174 offset:3072
	v_lshl_add_u64 v[210:211], s[58:59], 0, v[138:139]
	s_add_i32 m0, s61, 0xc000
	ds_read_b128 v[178:181], v153
	ds_read_b128 v[182:185], v153 offset:1024
	ds_read_b128 v[186:189], v153 offset:2048
	ds_read_b128 v[190:193], v153 offset:3072
	ds_read_b128 v[194:197], v153 offset:4096
	ds_read_b128 v[198:201], v153 offset:5120
	ds_read_b128 v[202:205], v153 offset:6144
	ds_read_b128 v[206:209], v153 offset:7168
	global_load_lds_dwordx4 v[210:211], off
	v_lshl_add_u64 v[210:211], s[58:59], 0, v[140:141]
	s_add_i32 m0, s61, 0xe000
	s_nop 0
	global_load_lds_dwordx4 v[210:211], off
	s_waitcnt vmcnt(8)
	s_waitcnt lgkmcnt(0)
	s_barrier
	s_setprio 1
	s_waitcnt lgkmcnt(0)
	v_mfma_f32_16x16x32_bf16 v[126:129], v[142:145], v[178:181], v[126:129]
	v_mfma_f32_16x16x32_bf16 v[118:121], v[154:157], v[178:181], v[118:121]
	v_mfma_f32_16x16x32_bf16 v[110:113], v[142:145], v[186:189], v[110:113]
	v_mfma_f32_16x16x32_bf16 v[102:105], v[154:157], v[186:189], v[102:105]
	v_mfma_f32_16x16x32_bf16 v[94:97], v[142:145], v[194:197], v[94:97]
	v_mfma_f32_16x16x32_bf16 v[86:89], v[154:157], v[194:197], v[86:89]
	v_mfma_f32_16x16x32_bf16 v[78:81], v[142:145], v[202:205], v[78:81]
	v_mfma_f32_16x16x32_bf16 v[70:73], v[154:157], v[202:205], v[70:73]
	v_mfma_f32_16x16x32_bf16 v[126:129], v[146:149], v[182:185], v[126:129]
	v_mfma_f32_16x16x32_bf16 v[118:121], v[158:161], v[182:185], v[118:121]
	v_mfma_f32_16x16x32_bf16 v[110:113], v[146:149], v[190:193], v[110:113]
	v_mfma_f32_16x16x32_bf16 v[102:105], v[158:161], v[190:193], v[102:105]
	v_mfma_f32_16x16x32_bf16 v[94:97], v[146:149], v[198:201], v[94:97]
	v_mfma_f32_16x16x32_bf16 v[86:89], v[158:161], v[198:201], v[86:89]
	v_mfma_f32_16x16x32_bf16 v[78:81], v[146:149], v[206:209], v[78:81]
	v_mfma_f32_16x16x32_bf16 v[70:73], v[158:161], v[206:209], v[70:73]
	v_mfma_f32_16x16x32_bf16 v[122:125], v[162:165], v[178:181], v[122:125]
	v_mfma_f32_16x16x32_bf16 v[114:117], v[170:173], v[178:181], v[114:117]
	v_mfma_f32_16x16x32_bf16 v[106:109], v[162:165], v[186:189], v[106:109]
	v_mfma_f32_16x16x32_bf16 v[98:101], v[170:173], v[186:189], v[98:101]
	v_mfma_f32_16x16x32_bf16 v[90:93], v[162:165], v[194:197], v[90:93]
	v_mfma_f32_16x16x32_bf16 v[82:85], v[170:173], v[194:197], v[82:85]
	v_mfma_f32_16x16x32_bf16 v[74:77], v[162:165], v[202:205], v[74:77]
	v_mfma_f32_16x16x32_bf16 v[66:69], v[170:173], v[202:205], v[66:69]
	v_mfma_f32_16x16x32_bf16 v[122:125], v[166:169], v[182:185], v[122:125]
	v_mfma_f32_16x16x32_bf16 v[114:117], v[174:177], v[182:185], v[114:117]
	v_mfma_f32_16x16x32_bf16 v[106:109], v[166:169], v[190:193], v[106:109]
	v_mfma_f32_16x16x32_bf16 v[98:101], v[174:177], v[190:193], v[98:101]
	v_mfma_f32_16x16x32_bf16 v[90:93], v[166:169], v[198:201], v[90:93]
	v_mfma_f32_16x16x32_bf16 v[82:85], v[174:177], v[198:201], v[82:85]
	v_mfma_f32_16x16x32_bf16 v[74:77], v[166:169], v[206:209], v[74:77]
	v_mfma_f32_16x16x32_bf16 v[66:69], v[174:177], v[206:209], v[66:69]
	s_setprio 0
	s_barrier
	s_add_i32 s8, s10, s31
	v_lshl_add_u64 v[210:211], s[28:29], 0, v[130:131]
	s_mov_b32 m0, s8
	ds_read_b128 v[178:181], v153 offset:16384
	ds_read_b128 v[182:185], v153 offset:17408
	ds_read_b128 v[186:189], v153 offset:18432
	ds_read_b128 v[190:193], v153 offset:19456
	ds_read_b128 v[194:197], v153 offset:20480
	ds_read_b128 v[198:201], v153 offset:21504
	ds_read_b128 v[202:205], v153 offset:22528
	ds_read_b128 v[206:209], v153 offset:23552
	global_load_lds_dwordx4 v[210:211], off
	s_add_i32 m0, s8, 0x2000
	s_add_u32 s8, s28, 0x40000
	v_lshl_add_u64 v[212:213], s[28:29], 0, v[132:133]
	s_addc_u32 s9, s29, 0
	s_add_i32 s10, s11, s31
	global_load_lds_dwordx4 v[212:213], off
	v_lshl_add_u64 v[214:215], s[8:9], 0, v[130:131]
	s_mov_b32 m0, s10
	v_lshl_add_u64 v[216:217], s[40:41], 0, v[134:135]
	global_load_lds_dwordx4 v[214:215], off
	v_lshl_add_u64 v[214:215], s[8:9], 0, v[132:133]
	s_add_i32 m0, s10, 0x2000
	s_nop 0
	global_load_lds_dwordx4 v[214:215], off
	v_lshl_add_u64 v[214:215], s[40:41], 0, v[136:137]
	s_mov_b32 m0, s61
	s_nop 0
	global_load_lds_dwordx4 v[214:215], off
	s_mov_b32 m0, s62
	s_nop 0
	global_load_lds_dwordx4 v[216:217], off
	s_waitcnt vmcnt(8)
	s_waitcnt lgkmcnt(0)
	s_barrier
	s_setprio 1
	s_waitcnt lgkmcnt(0)
	v_mfma_f32_16x16x32_bf16 v[62:65], v[142:145], v[178:181], v[62:65]
	v_mfma_f32_16x16x32_bf16 v[54:57], v[154:157], v[178:181], v[54:57]
	v_mfma_f32_16x16x32_bf16 v[46:49], v[142:145], v[186:189], v[46:49]
	v_mfma_f32_16x16x32_bf16 v[38:41], v[154:157], v[186:189], v[38:41]
	v_mfma_f32_16x16x32_bf16 v[30:33], v[142:145], v[194:197], v[30:33]
	v_mfma_f32_16x16x32_bf16 v[22:25], v[154:157], v[194:197], v[22:25]
	v_mfma_f32_16x16x32_bf16 v[14:17], v[142:145], v[202:205], v[14:17]
	v_mfma_f32_16x16x32_bf16 v[6:9], v[154:157], v[202:205], v[6:9]
	v_mfma_f32_16x16x32_bf16 v[62:65], v[146:149], v[182:185], v[62:65]
	v_mfma_f32_16x16x32_bf16 v[54:57], v[158:161], v[182:185], v[54:57]
	v_mfma_f32_16x16x32_bf16 v[46:49], v[146:149], v[190:193], v[46:49]
	v_mfma_f32_16x16x32_bf16 v[38:41], v[158:161], v[190:193], v[38:41]
	v_mfma_f32_16x16x32_bf16 v[30:33], v[146:149], v[198:201], v[30:33]
	v_mfma_f32_16x16x32_bf16 v[22:25], v[158:161], v[198:201], v[22:25]
	v_mfma_f32_16x16x32_bf16 v[14:17], v[146:149], v[206:209], v[14:17]
	v_mfma_f32_16x16x32_bf16 v[6:9], v[158:161], v[206:209], v[6:9]
	v_mfma_f32_16x16x32_bf16 v[58:61], v[162:165], v[178:181], v[58:61]
	v_mfma_f32_16x16x32_bf16 v[50:53], v[170:173], v[178:181], v[50:53]
	v_mfma_f32_16x16x32_bf16 v[42:45], v[162:165], v[186:189], v[42:45]
	v_mfma_f32_16x16x32_bf16 v[34:37], v[170:173], v[186:189], v[34:37]
	v_mfma_f32_16x16x32_bf16 v[26:29], v[162:165], v[194:197], v[26:29]
	v_mfma_f32_16x16x32_bf16 v[18:21], v[170:173], v[194:197], v[18:21]
	v_mfma_f32_16x16x32_bf16 v[10:13], v[162:165], v[202:205], v[10:13]
	v_mfma_f32_16x16x32_bf16 v[2:5], v[170:173], v[202:205], v[2:5]
	v_mfma_f32_16x16x32_bf16 v[58:61], v[166:169], v[182:185], v[58:61]
	v_mfma_f32_16x16x32_bf16 v[50:53], v[174:177], v[182:185], v[50:53]
	v_mfma_f32_16x16x32_bf16 v[42:45], v[166:169], v[190:193], v[42:45]
	v_mfma_f32_16x16x32_bf16 v[34:37], v[174:177], v[190:193], v[34:37]
	v_mfma_f32_16x16x32_bf16 v[26:29], v[166:169], v[198:201], v[26:29]
	v_mfma_f32_16x16x32_bf16 v[18:21], v[174:177], v[198:201], v[18:21]
	v_mfma_f32_16x16x32_bf16 v[10:13], v[166:169], v[206:209], v[10:13]
	v_mfma_f32_16x16x32_bf16 v[2:5], v[174:177], v[206:209], v[2:5]
	s_setprio 0
	s_barrier
	s_add_i32 s10, 0, 0x18000
	s_add_i32 s11, 0, 0x1c000
	v_add_u32_e32 v158, s10, v150
	v_add_u32_e32 v174, s11, v150
	ds_read_b128 v[142:145], v158
	ds_read_b128 v[146:149], v158 offset:1024
	ds_read_b128 v[154:157], v158 offset:2048
	ds_read_b128 v[158:161], v158 offset:3072
	ds_read_b128 v[162:165], v174
	ds_read_b128 v[166:169], v174 offset:1024
	ds_read_b128 v[170:173], v174 offset:2048
	ds_read_b128 v[174:177], v174 offset:3072
	s_add_u32 s8, s40, 0x40000
	s_addc_u32 s9, s41, 0
	s_mov_b32 m0, s63
	v_lshl_add_u64 v[218:219], s[8:9], 0, v[136:137]
	ds_read_b128 v[178:181], v153 offset:32768
	ds_read_b128 v[182:185], v153 offset:33792
	ds_read_b128 v[186:189], v153 offset:34816
	ds_read_b128 v[190:193], v153 offset:35840
	ds_read_b128 v[194:197], v153 offset:36864
	ds_read_b128 v[198:201], v153 offset:37888
	ds_read_b128 v[202:205], v153 offset:38912
	ds_read_b128 v[206:209], v153 offset:39936
	global_load_lds_dwordx4 v[218:219], off
	v_lshl_add_u64 v[218:219], s[8:9], 0, v[134:135]
	s_mov_b32 m0, s64
	s_nop 0
	global_load_lds_dwordx4 v[218:219], off
	s_waitcnt vmcnt(8)
	s_waitcnt lgkmcnt(0)
	s_barrier
	s_setprio 1
	s_waitcnt lgkmcnt(0)
	v_mfma_f32_16x16x32_bf16 v[126:129], v[142:145], v[178:181], v[126:129]
	v_mfma_f32_16x16x32_bf16 v[118:121], v[154:157], v[178:181], v[118:121]
	v_mfma_f32_16x16x32_bf16 v[110:113], v[142:145], v[186:189], v[110:113]
	v_mfma_f32_16x16x32_bf16 v[102:105], v[154:157], v[186:189], v[102:105]
	v_mfma_f32_16x16x32_bf16 v[94:97], v[142:145], v[194:197], v[94:97]
	v_mfma_f32_16x16x32_bf16 v[86:89], v[154:157], v[194:197], v[86:89]
	v_mfma_f32_16x16x32_bf16 v[78:81], v[142:145], v[202:205], v[78:81]
	v_mfma_f32_16x16x32_bf16 v[70:73], v[154:157], v[202:205], v[70:73]
	v_mfma_f32_16x16x32_bf16 v[126:129], v[146:149], v[182:185], v[126:129]
	v_mfma_f32_16x16x32_bf16 v[118:121], v[158:161], v[182:185], v[118:121]
	v_mfma_f32_16x16x32_bf16 v[110:113], v[146:149], v[190:193], v[110:113]
	v_mfma_f32_16x16x32_bf16 v[102:105], v[158:161], v[190:193], v[102:105]
	v_mfma_f32_16x16x32_bf16 v[94:97], v[146:149], v[198:201], v[94:97]
	v_mfma_f32_16x16x32_bf16 v[86:89], v[158:161], v[198:201], v[86:89]
	v_mfma_f32_16x16x32_bf16 v[78:81], v[146:149], v[206:209], v[78:81]
	v_mfma_f32_16x16x32_bf16 v[70:73], v[158:161], v[206:209], v[70:73]
	v_mfma_f32_16x16x32_bf16 v[122:125], v[162:165], v[178:181], v[122:125]
	v_mfma_f32_16x16x32_bf16 v[114:117], v[170:173], v[178:181], v[114:117]
	v_mfma_f32_16x16x32_bf16 v[106:109], v[162:165], v[186:189], v[106:109]
	v_mfma_f32_16x16x32_bf16 v[98:101], v[170:173], v[186:189], v[98:101]
	v_mfma_f32_16x16x32_bf16 v[90:93], v[162:165], v[194:197], v[90:93]
	v_mfma_f32_16x16x32_bf16 v[82:85], v[170:173], v[194:197], v[82:85]
	v_mfma_f32_16x16x32_bf16 v[74:77], v[162:165], v[202:205], v[74:77]
	v_mfma_f32_16x16x32_bf16 v[66:69], v[170:173], v[202:205], v[66:69]
	v_mfma_f32_16x16x32_bf16 v[122:125], v[166:169], v[182:185], v[122:125]
	v_mfma_f32_16x16x32_bf16 v[114:117], v[174:177], v[182:185], v[114:117]
	v_mfma_f32_16x16x32_bf16 v[106:109], v[166:169], v[190:193], v[106:109]
	v_mfma_f32_16x16x32_bf16 v[98:101], v[174:177], v[190:193], v[98:101]
	v_mfma_f32_16x16x32_bf16 v[90:93], v[166:169], v[198:201], v[90:93]
	v_mfma_f32_16x16x32_bf16 v[82:85], v[174:177], v[198:201], v[82:85]
	v_mfma_f32_16x16x32_bf16 v[74:77], v[166:169], v[206:209], v[74:77]
	v_mfma_f32_16x16x32_bf16 v[66:69], v[174:177], v[206:209], v[66:69]
	s_setprio 0
	s_barrier
	s_add_i32 s8, s10, s31
	v_lshl_add_u64 v[210:211], v[210:211], 0, s[82:83]
	s_mov_b32 m0, s8
	ds_read_b128 v[178:181], v153 offset:49152
	ds_read_b128 v[182:185], v153 offset:50176
	ds_read_b128 v[186:189], v153 offset:51200
	ds_read_b128 v[190:193], v153 offset:52224
	ds_read_b128 v[194:197], v153 offset:53248
	ds_read_b128 v[198:201], v153 offset:54272
	ds_read_b128 v[202:205], v153 offset:55296
	ds_read_b128 v[206:209], v153 offset:56320
	global_load_lds_dwordx4 v[210:211], off
	s_add_i32 m0, s8, 0x2000
	s_add_u32 s8, s28, 0x40080
	v_lshl_add_u64 v[210:211], v[212:213], 0, s[82:83]
	s_addc_u32 s9, s29, 0
	s_add_i32 s10, s11, s31
	global_load_lds_dwordx4 v[210:211], off
	v_lshl_add_u64 v[210:211], s[8:9], 0, v[130:131]
	s_mov_b32 m0, s10
	s_nop 0
	global_load_lds_dwordx4 v[210:211], off
	v_lshl_add_u64 v[210:211], s[8:9], 0, v[132:133]
	s_add_i32 m0, s10, 0x2000
	s_nop 0
	global_load_lds_dwordx4 v[210:211], off
	v_lshl_add_u64 v[210:211], v[214:215], 0, s[82:83]
	s_mov_b32 m0, s65
	s_nop 0
	global_load_lds_dwordx4 v[210:211], off
	v_lshl_add_u64 v[210:211], v[216:217], 0, s[82:83]
	s_mov_b32 m0, s66
	s_nop 0
	global_load_lds_dwordx4 v[210:211], off
	s_waitcnt vmcnt(8)
	s_waitcnt lgkmcnt(0)
	s_barrier
	s_setprio 1
	s_waitcnt lgkmcnt(0)
	v_mfma_f32_16x16x32_bf16 v[62:65], v[142:145], v[178:181], v[62:65]
	v_mfma_f32_16x16x32_bf16 v[54:57], v[154:157], v[178:181], v[54:57]
	v_mfma_f32_16x16x32_bf16 v[46:49], v[142:145], v[186:189], v[46:49]
	v_mfma_f32_16x16x32_bf16 v[38:41], v[154:157], v[186:189], v[38:41]
	v_mfma_f32_16x16x32_bf16 v[30:33], v[142:145], v[194:197], v[30:33]
	v_mfma_f32_16x16x32_bf16 v[22:25], v[154:157], v[194:197], v[22:25]
	v_mfma_f32_16x16x32_bf16 v[14:17], v[142:145], v[202:205], v[14:17]
	v_mfma_f32_16x16x32_bf16 v[6:9], v[154:157], v[202:205], v[6:9]
	v_mfma_f32_16x16x32_bf16 v[62:65], v[146:149], v[182:185], v[62:65]
	v_mfma_f32_16x16x32_bf16 v[54:57], v[158:161], v[182:185], v[54:57]
	v_mfma_f32_16x16x32_bf16 v[46:49], v[146:149], v[190:193], v[46:49]
	v_mfma_f32_16x16x32_bf16 v[38:41], v[158:161], v[190:193], v[38:41]
	v_mfma_f32_16x16x32_bf16 v[30:33], v[146:149], v[198:201], v[30:33]
	v_mfma_f32_16x16x32_bf16 v[22:25], v[158:161], v[198:201], v[22:25]
	v_mfma_f32_16x16x32_bf16 v[14:17], v[146:149], v[206:209], v[14:17]
	v_mfma_f32_16x16x32_bf16 v[6:9], v[158:161], v[206:209], v[6:9]
	v_mfma_f32_16x16x32_bf16 v[58:61], v[162:165], v[178:181], v[58:61]
	v_mfma_f32_16x16x32_bf16 v[50:53], v[170:173], v[178:181], v[50:53]
	v_mfma_f32_16x16x32_bf16 v[42:45], v[162:165], v[186:189], v[42:45]
	v_mfma_f32_16x16x32_bf16 v[34:37], v[170:173], v[186:189], v[34:37]
	v_mfma_f32_16x16x32_bf16 v[26:29], v[162:165], v[194:197], v[26:29]
	v_mfma_f32_16x16x32_bf16 v[18:21], v[170:173], v[194:197], v[18:21]
	v_mfma_f32_16x16x32_bf16 v[10:13], v[162:165], v[202:205], v[10:13]
	v_mfma_f32_16x16x32_bf16 v[2:5], v[170:173], v[202:205], v[2:5]
	v_mfma_f32_16x16x32_bf16 v[58:61], v[166:169], v[182:185], v[58:61]
	v_mfma_f32_16x16x32_bf16 v[50:53], v[174:177], v[182:185], v[50:53]
	v_mfma_f32_16x16x32_bf16 v[42:45], v[166:169], v[190:193], v[42:45]
	v_mfma_f32_16x16x32_bf16 v[34:37], v[174:177], v[190:193], v[34:37]
	v_mfma_f32_16x16x32_bf16 v[26:29], v[166:169], v[198:201], v[26:29]
	v_mfma_f32_16x16x32_bf16 v[18:21], v[174:177], v[198:201], v[18:21]
	v_mfma_f32_16x16x32_bf16 v[10:13], v[166:169], v[206:209], v[10:13]
	v_mfma_f32_16x16x32_bf16 v[2:5], v[174:177], v[206:209], v[2:5]
	s_setprio 0
	s_barrier
	s_add_i32 s85, s85, 2
	s_add_u32 s58, s58, 0x100
	s_addc_u32 s59, s59, 0
	s_add_u32 s73, s73, 0x100
	s_addc_u32 s84, s84, 0
	s_cmp_gt_u32 s85, 13
	s_cbranch_scc0 .LBB0_50
	s_and_b64 vcc, exec, s[48:49]
	s_cbranch_vccz .LBB0_53
	s_barrier

.LBB0_75:
	s_add_i32 s41, s28, 2
	s_add_u32 s8, s60, 0x80
	s_addc_u32 s9, s61, 0
	s_add_i32 s10, 0, 0x10000
	s_cmp_eq_u32 s84, s28
	s_cselect_b32 s29, s47, s9
	s_cselect_b32 s28, s46, s8
	s_cselect_b32 s9, s59, s40
	s_cselect_b32 s8, s58, s7
	s_add_i32 s11, 0, 0x14000
	v_add_u32_e32 v126, s10, v1
	v_add_u32_e32 v160, s11, v1
	ds_read_b128 v[98:101], v126
	ds_read_b128 v[102:105], v126 offset:1024
	ds_read_b128 v[122:125], v126 offset:2048
	ds_read_b128 v[126:129], v126 offset:3072
	ds_read_b128 v[144:147], v160
	ds_read_b128 v[148:151], v160 offset:1024
	ds_read_b128 v[156:159], v160 offset:2048
	ds_read_b128 v[160:163], v160 offset:3072
	v_lshl_add_u64 v[206:207], s[60:61], 0, v[194:195]
	s_add_i32 m0, s66, 0xc000
	ds_read_b128 v[164:167], v231
	ds_read_b128 v[168:171], v231 offset:1024
	ds_read_b128 v[172:175], v231 offset:2048
	ds_read_b128 v[176:179], v231 offset:3072
	ds_read_b128 v[180:183], v231 offset:4096
	ds_read_b128 v[184:187], v231 offset:5120
	ds_read_b128 v[198:201], v231 offset:6144
	ds_read_b128 v[202:205], v231 offset:7168
	global_load_lds_dwordx4 v[206:207], off
	v_lshl_add_u64 v[206:207], s[60:61], 0, v[196:197]
	s_add_i32 m0, s66, 0xe000
	s_nop 0
	global_load_lds_dwordx4 v[206:207], off
	s_waitcnt vmcnt(8)
	s_waitcnt lgkmcnt(0)
	s_barrier
	s_setprio 1
	s_waitcnt lgkmcnt(0)
	v_mfma_f32_16x16x32_bf16 v[152:155], v[98:101], v[164:167], v[152:155]
	v_mfma_f32_16x16x32_bf16 v[140:143], v[122:125], v[164:167], v[140:143]
	v_mfma_f32_16x16x32_bf16 v[118:121], v[98:101], v[172:175], v[118:121]
	v_mfma_f32_16x16x32_bf16 v[114:117], v[122:125], v[172:175], v[114:117]
	v_mfma_f32_16x16x32_bf16 v[94:97], v[98:101], v[180:183], v[94:97]
	v_mfma_f32_16x16x32_bf16 v[90:93], v[122:125], v[180:183], v[90:93]
	v_mfma_f32_16x16x32_bf16 v[78:81], v[98:101], v[198:201], v[78:81]
	v_mfma_f32_16x16x32_bf16 v[74:77], v[122:125], v[198:201], v[74:77]
	v_mfma_f32_16x16x32_bf16 v[152:155], v[102:105], v[168:171], v[152:155]
	v_mfma_f32_16x16x32_bf16 v[140:143], v[126:129], v[168:171], v[140:143]
	v_mfma_f32_16x16x32_bf16 v[118:121], v[102:105], v[176:179], v[118:121]
	v_mfma_f32_16x16x32_bf16 v[114:117], v[126:129], v[176:179], v[114:117]
	v_mfma_f32_16x16x32_bf16 v[94:97], v[102:105], v[184:187], v[94:97]
	v_mfma_f32_16x16x32_bf16 v[90:93], v[126:129], v[184:187], v[90:93]
	v_mfma_f32_16x16x32_bf16 v[78:81], v[102:105], v[202:205], v[78:81]
	v_mfma_f32_16x16x32_bf16 v[74:77], v[126:129], v[202:205], v[74:77]
	v_mfma_f32_16x16x32_bf16 v[136:139], v[144:147], v[164:167], v[136:139]
	v_mfma_f32_16x16x32_bf16 v[132:135], v[156:159], v[164:167], v[132:135]
	v_mfma_f32_16x16x32_bf16 v[110:113], v[144:147], v[172:175], v[110:113]
	v_mfma_f32_16x16x32_bf16 v[106:109], v[156:159], v[172:175], v[106:109]
	v_mfma_f32_16x16x32_bf16 v[86:89], v[144:147], v[180:183], v[86:89]
	v_mfma_f32_16x16x32_bf16 v[82:85], v[156:159], v[180:183], v[82:85]
	v_mfma_f32_16x16x32_bf16 v[70:73], v[144:147], v[198:201], v[70:73]
	v_mfma_f32_16x16x32_bf16 v[66:69], v[156:159], v[198:201], v[66:69]
	v_mfma_f32_16x16x32_bf16 v[136:139], v[148:151], v[168:171], v[136:139]
	v_mfma_f32_16x16x32_bf16 v[132:135], v[160:163], v[168:171], v[132:135]
	v_mfma_f32_16x16x32_bf16 v[110:113], v[148:151], v[176:179], v[110:113]
	v_mfma_f32_16x16x32_bf16 v[106:109], v[160:163], v[176:179], v[106:109]
	v_mfma_f32_16x16x32_bf16 v[86:89], v[148:151], v[184:187], v[86:89]
	v_mfma_f32_16x16x32_bf16 v[82:85], v[160:163], v[184:187], v[82:85]
	v_mfma_f32_16x16x32_bf16 v[70:73], v[148:151], v[202:205], v[70:73]
	v_mfma_f32_16x16x32_bf16 v[66:69], v[160:163], v[202:205], v[66:69]
	s_setprio 0
	s_barrier
	s_add_i32 s10, s10, s64
	v_lshl_add_u64 v[206:207], s[8:9], 0, v[130:131]
	s_mov_b32 m0, s10
	ds_read_b128 v[164:167], v231 offset:16384
	ds_read_b128 v[168:171], v231 offset:17408
	ds_read_b128 v[172:175], v231 offset:18432
	ds_read_b128 v[176:179], v231 offset:19456
	ds_read_b128 v[180:183], v231 offset:20480
	ds_read_b128 v[184:187], v231 offset:21504
	ds_read_b128 v[198:201], v231 offset:22528
	ds_read_b128 v[202:205], v231 offset:23552
	global_load_lds_dwordx4 v[206:207], off
	s_add_i32 m0, s10, 0x2000
	v_lshl_add_u64 v[208:209], s[8:9], 0, v[188:189]
	s_add_u32 s8, s8, s48
	s_addc_u32 s9, s9, 0
	s_add_i32 s10, s11, s64
	global_load_lds_dwordx4 v[208:209], off
	v_lshl_add_u64 v[210:211], s[8:9], 0, v[130:131]
	s_mov_b32 m0, s10
	v_lshl_add_u64 v[212:213], s[8:9], 0, v[188:189]
	global_load_lds_dwordx4 v[210:211], off
	s_add_i32 m0, s10, 0x2000
	v_lshl_add_u64 v[214:215], s[28:29], 0, v[192:193]
	global_load_lds_dwordx4 v[212:213], off
	s_mov_b32 m0, s66
	v_lshl_add_u64 v[216:217], s[28:29], 0, v[190:191]
	global_load_lds_dwordx4 v[214:215], off
	s_mov_b32 m0, s67
	s_nop 0
	global_load_lds_dwordx4 v[216:217], off
	s_waitcnt vmcnt(8)
	s_waitcnt lgkmcnt(0)
	s_barrier
	s_setprio 1
	s_waitcnt lgkmcnt(0)
	v_mfma_f32_16x16x32_bf16 v[62:65], v[98:101], v[164:167], v[62:65]
	v_mfma_f32_16x16x32_bf16 v[58:61], v[122:125], v[164:167], v[58:61]
	v_mfma_f32_16x16x32_bf16 v[46:49], v[98:101], v[172:175], v[46:49]
	v_mfma_f32_16x16x32_bf16 v[42:45], v[122:125], v[172:175], v[42:45]
	v_mfma_f32_16x16x32_bf16 v[30:33], v[98:101], v[180:183], v[30:33]
	v_mfma_f32_16x16x32_bf16 v[26:29], v[122:125], v[180:183], v[26:29]
	v_mfma_f32_16x16x32_bf16 v[14:17], v[98:101], v[198:201], v[14:17]
	v_mfma_f32_16x16x32_bf16 v[10:13], v[122:125], v[198:201], v[10:13]
	v_mfma_f32_16x16x32_bf16 v[62:65], v[102:105], v[168:171], v[62:65]
	v_mfma_f32_16x16x32_bf16 v[58:61], v[126:129], v[168:171], v[58:61]
	v_mfma_f32_16x16x32_bf16 v[46:49], v[102:105], v[176:179], v[46:49]
	v_mfma_f32_16x16x32_bf16 v[42:45], v[126:129], v[176:179], v[42:45]
	v_mfma_f32_16x16x32_bf16 v[30:33], v[102:105], v[184:187], v[30:33]
	v_mfma_f32_16x16x32_bf16 v[26:29], v[126:129], v[184:187], v[26:29]
	v_mfma_f32_16x16x32_bf16 v[14:17], v[102:105], v[202:205], v[14:17]
	v_mfma_f32_16x16x32_bf16 v[10:13], v[126:129], v[202:205], v[10:13]
	v_mfma_f32_16x16x32_bf16 v[54:57], v[144:147], v[164:167], v[54:57]
	v_mfma_f32_16x16x32_bf16 v[50:53], v[156:159], v[164:167], v[50:53]
	v_mfma_f32_16x16x32_bf16 v[38:41], v[144:147], v[172:175], v[38:41]
	v_mfma_f32_16x16x32_bf16 v[34:37], v[156:159], v[172:175], v[34:37]
	v_mfma_f32_16x16x32_bf16 v[22:25], v[144:147], v[180:183], v[22:25]
	v_mfma_f32_16x16x32_bf16 v[18:21], v[156:159], v[180:183], v[18:21]
	v_mfma_f32_16x16x32_bf16 v[6:9], v[144:147], v[198:201], v[6:9]
	v_mfma_f32_16x16x32_bf16 v[2:5], v[156:159], v[198:201], v[2:5]
	v_mfma_f32_16x16x32_bf16 v[54:57], v[148:151], v[168:171], v[54:57]
	v_mfma_f32_16x16x32_bf16 v[50:53], v[160:163], v[168:171], v[50:53]
	v_mfma_f32_16x16x32_bf16 v[38:41], v[148:151], v[176:179], v[38:41]
	v_mfma_f32_16x16x32_bf16 v[34:37], v[160:163], v[176:179], v[34:37]
	v_mfma_f32_16x16x32_bf16 v[22:25], v[148:151], v[184:187], v[22:25]
	v_mfma_f32_16x16x32_bf16 v[18:21], v[160:163], v[184:187], v[18:21]
	v_mfma_f32_16x16x32_bf16 v[6:9], v[148:151], v[202:205], v[6:9]
	v_mfma_f32_16x16x32_bf16 v[2:5], v[160:163], v[202:205], v[2:5]
	s_setprio 0
	s_barrier
	s_add_i32 s10, 0, 0x18000
	s_add_i32 s11, 0, 0x1c000
	v_add_u32_e32 v126, s10, v1
	v_add_u32_e32 v160, s11, v1
	ds_read_b128 v[98:101], v126
	ds_read_b128 v[102:105], v126 offset:1024
	ds_read_b128 v[122:125], v126 offset:2048
	ds_read_b128 v[126:129], v126 offset:3072
	ds_read_b128 v[144:147], v160
	ds_read_b128 v[148:151], v160 offset:1024
	ds_read_b128 v[156:159], v160 offset:2048
	ds_read_b128 v[160:163], v160 offset:3072
	s_add_u32 s8, s28, s48
	s_addc_u32 s9, s29, 0
	s_mov_b32 m0, s68
	v_lshl_add_u64 v[218:219], s[8:9], 0, v[192:193]
	ds_read_b128 v[164:167], v231 offset:32768
	ds_read_b128 v[168:171], v231 offset:33792
	ds_read_b128 v[172:175], v231 offset:34816
	ds_read_b128 v[176:179], v231 offset:35840
	ds_read_b128 v[180:183], v231 offset:36864
	ds_read_b128 v[184:187], v231 offset:37888
	ds_read_b128 v[198:201], v231 offset:38912
	ds_read_b128 v[202:205], v231 offset:39936
	global_load_lds_dwordx4 v[218:219], off
	v_lshl_add_u64 v[218:219], s[8:9], 0, v[190:191]
	s_mov_b32 m0, s69
	s_nop 0
	global_load_lds_dwordx4 v[218:219], off
	s_waitcnt vmcnt(8)
	s_waitcnt lgkmcnt(0)
	s_barrier
	s_setprio 1
	s_waitcnt lgkmcnt(0)
	v_mfma_f32_16x16x32_bf16 v[152:155], v[98:101], v[164:167], v[152:155]
	v_mfma_f32_16x16x32_bf16 v[140:143], v[122:125], v[164:167], v[140:143]
	v_mfma_f32_16x16x32_bf16 v[118:121], v[98:101], v[172:175], v[118:121]
	v_mfma_f32_16x16x32_bf16 v[114:117], v[122:125], v[172:175], v[114:117]
	v_mfma_f32_16x16x32_bf16 v[94:97], v[98:101], v[180:183], v[94:97]
	v_mfma_f32_16x16x32_bf16 v[90:93], v[122:125], v[180:183], v[90:93]
	v_mfma_f32_16x16x32_bf16 v[78:81], v[98:101], v[198:201], v[78:81]
	v_mfma_f32_16x16x32_bf16 v[74:77], v[122:125], v[198:201], v[74:77]
	v_mfma_f32_16x16x32_bf16 v[152:155], v[102:105], v[168:171], v[152:155]
	v_mfma_f32_16x16x32_bf16 v[140:143], v[126:129], v[168:171], v[140:143]
	v_mfma_f32_16x16x32_bf16 v[118:121], v[102:105], v[176:179], v[118:121]
	v_mfma_f32_16x16x32_bf16 v[114:117], v[126:129], v[176:179], v[114:117]
	v_mfma_f32_16x16x32_bf16 v[94:97], v[102:105], v[184:187], v[94:97]
	v_mfma_f32_16x16x32_bf16 v[90:93], v[126:129], v[184:187], v[90:93]
	v_mfma_f32_16x16x32_bf16 v[78:81], v[102:105], v[202:205], v[78:81]
	v_mfma_f32_16x16x32_bf16 v[74:77], v[126:129], v[202:205], v[74:77]
	v_mfma_f32_16x16x32_bf16 v[136:139], v[144:147], v[164:167], v[136:139]
	v_mfma_f32_16x16x32_bf16 v[132:135], v[156:159], v[164:167], v[132:135]
	v_mfma_f32_16x16x32_bf16 v[110:113], v[144:147], v[172:175], v[110:113]
	v_mfma_f32_16x16x32_bf16 v[106:109], v[156:159], v[172:175], v[106:109]
	v_mfma_f32_16x16x32_bf16 v[86:89], v[144:147], v[180:183], v[86:89]
	v_mfma_f32_16x16x32_bf16 v[82:85], v[156:159], v[180:183], v[82:85]
	v_mfma_f32_16x16x32_bf16 v[70:73], v[144:147], v[198:201], v[70:73]
	v_mfma_f32_16x16x32_bf16 v[66:69], v[156:159], v[198:201], v[66:69]
	v_mfma_f32_16x16x32_bf16 v[136:139], v[148:151], v[168:171], v[136:139]
	v_mfma_f32_16x16x32_bf16 v[132:135], v[160:163], v[168:171], v[132:135]
	v_mfma_f32_16x16x32_bf16 v[110:113], v[148:151], v[176:179], v[110:113]
	v_mfma_f32_16x16x32_bf16 v[106:109], v[160:163], v[176:179], v[106:109]
	v_mfma_f32_16x16x32_bf16 v[86:89], v[148:151], v[184:187], v[86:89]
	v_mfma_f32_16x16x32_bf16 v[82:85], v[160:163], v[184:187], v[82:85]
	v_mfma_f32_16x16x32_bf16 v[70:73], v[148:151], v[202:205], v[70:73]
	v_mfma_f32_16x16x32_bf16 v[66:69], v[160:163], v[202:205], v[66:69]
	s_setprio 0
	s_barrier
	s_add_i32 s8, s10, s64
	v_lshl_add_u64 v[206:207], v[206:207], 0, s[82:83]
	s_mov_b32 m0, s8
	ds_read_b128 v[164:167], v231 offset:49152
	ds_read_b128 v[168:171], v231 offset:50176
	ds_read_b128 v[172:175], v231 offset:51200
	ds_read_b128 v[176:179], v231 offset:52224
	ds_read_b128 v[180:183], v231 offset:53248
	ds_read_b128 v[184:187], v231 offset:54272
	ds_read_b128 v[198:201], v231 offset:55296
	ds_read_b128 v[202:205], v231 offset:56320
	global_load_lds_dwordx4 v[206:207], off
	v_lshl_add_u64 v[206:207], v[208:209], 0, s[82:83]
	s_add_i32 m0, s8, 0x2000
	s_add_i32 s8, s11, s64
	global_load_lds_dwordx4 v[206:207], off
	v_lshl_add_u64 v[206:207], v[210:211], 0, s[82:83]
	s_mov_b32 m0, s8
	s_nop 0
	global_load_lds_dwordx4 v[206:207], off
	v_lshl_add_u64 v[206:207], v[212:213], 0, s[82:83]
	s_add_i32 m0, s8, 0x2000
	s_nop 0
	global_load_lds_dwordx4 v[206:207], off
	v_lshl_add_u64 v[206:207], v[214:215], 0, s[82:83]
	s_mov_b32 m0, s85
	s_nop 0
	global_load_lds_dwordx4 v[206:207], off
	v_lshl_add_u64 v[206:207], v[216:217], 0, s[82:83]
	s_mov_b32 m0, s88
	s_nop 0
	global_load_lds_dwordx4 v[206:207], off
	s_waitcnt vmcnt(8)
	s_waitcnt lgkmcnt(0)
	s_barrier
	s_setprio 1
	s_waitcnt lgkmcnt(0)
	v_mfma_f32_16x16x32_bf16 v[62:65], v[98:101], v[164:167], v[62:65]
	v_mfma_f32_16x16x32_bf16 v[58:61], v[122:125], v[164:167], v[58:61]
	v_mfma_f32_16x16x32_bf16 v[46:49], v[98:101], v[172:175], v[46:49]
	v_mfma_f32_16x16x32_bf16 v[42:45], v[122:125], v[172:175], v[42:45]
	v_mfma_f32_16x16x32_bf16 v[30:33], v[98:101], v[180:183], v[30:33]
	v_mfma_f32_16x16x32_bf16 v[26:29], v[122:125], v[180:183], v[26:29]
	v_mfma_f32_16x16x32_bf16 v[14:17], v[98:101], v[198:201], v[14:17]
	v_mfma_f32_16x16x32_bf16 v[10:13], v[122:125], v[198:201], v[10:13]
	v_mfma_f32_16x16x32_bf16 v[62:65], v[102:105], v[168:171], v[62:65]
	v_mfma_f32_16x16x32_bf16 v[58:61], v[126:129], v[168:171], v[58:61]
	v_mfma_f32_16x16x32_bf16 v[46:49], v[102:105], v[176:179], v[46:49]
	v_mfma_f32_16x16x32_bf16 v[42:45], v[126:129], v[176:179], v[42:45]
	v_mfma_f32_16x16x32_bf16 v[30:33], v[102:105], v[184:187], v[30:33]
	v_mfma_f32_16x16x32_bf16 v[26:29], v[126:129], v[184:187], v[26:29]
	v_mfma_f32_16x16x32_bf16 v[14:17], v[102:105], v[202:205], v[14:17]
	v_mfma_f32_16x16x32_bf16 v[10:13], v[126:129], v[202:205], v[10:13]
	v_mfma_f32_16x16x32_bf16 v[54:57], v[144:147], v[164:167], v[54:57]
	v_mfma_f32_16x16x32_bf16 v[50:53], v[156:159], v[164:167], v[50:53]
	v_mfma_f32_16x16x32_bf16 v[38:41], v[144:147], v[172:175], v[38:41]
	v_mfma_f32_16x16x32_bf16 v[34:37], v[156:159], v[172:175], v[34:37]
	v_mfma_f32_16x16x32_bf16 v[22:25], v[144:147], v[180:183], v[22:25]
	v_mfma_f32_16x16x32_bf16 v[18:21], v[156:159], v[180:183], v[18:21]
	v_mfma_f32_16x16x32_bf16 v[6:9], v[144:147], v[198:201], v[6:9]
	v_mfma_f32_16x16x32_bf16 v[2:5], v[156:159], v[198:201], v[2:5]
	v_mfma_f32_16x16x32_bf16 v[54:57], v[148:151], v[168:171], v[54:57]
	v_mfma_f32_16x16x32_bf16 v[50:53], v[160:163], v[168:171], v[50:53]
	v_mfma_f32_16x16x32_bf16 v[38:41], v[148:151], v[176:179], v[38:41]
	v_mfma_f32_16x16x32_bf16 v[34:37], v[160:163], v[176:179], v[34:37]
	v_mfma_f32_16x16x32_bf16 v[22:25], v[148:151], v[184:187], v[22:25]
	v_mfma_f32_16x16x32_bf16 v[18:21], v[160:163], v[184:187], v[18:21]
	v_mfma_f32_16x16x32_bf16 v[6:9], v[148:151], v[202:205], v[6:9]
	v_mfma_f32_16x16x32_bf16 v[2:5], v[160:163], v[202:205], v[2:5]
	s_setprio 0
	s_barrier
	s_add_u32 s60, s60, 0x100
	s_addc_u32 s61, s61, 0
	s_add_u32 s7, s7, 0x100
	s_addc_u32 s40, s40, 0
	s_cmp_ge_u32 s41, s73
	s_mov_b32 s28, s41
	s_cbranch_scc0 .LBB0_75
	s_and_b64 vcc, exec, s[54:55]
	s_cbranch_vccz .LBB0_78
	s_barrier

.LBB0_497:
	s_add_u32 s8, s60, 0xfffc0080
	s_addc_u32 s9, s61, -1
	s_add_i32 s10, 0, 0x10000
	s_cmp_eq_u32 s84, 12
	s_cselect_b32 s41, s55, s9
	s_cselect_b32 s40, s72, s8
	s_cselect_b32 s29, s53, s77
	s_cselect_b32 s28, s73, s76
	s_add_i32 s11, 0, 0x14000
	v_add_u32_e32 v158, s10, v1
	v_add_u32_e32 v174, s11, v1
	ds_read_b128 v[146:149], v158
	ds_read_b128 v[150:153], v158 offset:1024
	ds_read_b128 v[154:157], v158 offset:2048
	ds_read_b128 v[158:161], v158 offset:3072
	ds_read_b128 v[162:165], v174
	ds_read_b128 v[166:169], v174 offset:1024
	ds_read_b128 v[170:173], v174 offset:2048
	ds_read_b128 v[174:177], v174 offset:3072
	v_lshl_add_u64 v[210:211], s[60:61], 0, v[138:139]
	s_add_i32 m0, s62, 0xc000
	ds_read_b128 v[178:181], v145
	ds_read_b128 v[182:185], v145 offset:1024
	ds_read_b128 v[186:189], v145 offset:2048
	ds_read_b128 v[190:193], v145 offset:3072
	ds_read_b128 v[194:197], v145 offset:4096
	ds_read_b128 v[198:201], v145 offset:5120
	ds_read_b128 v[202:205], v145 offset:6144
	ds_read_b128 v[206:209], v145 offset:7168
	global_load_lds_dwordx4 v[210:211], off
	v_lshl_add_u64 v[210:211], s[60:61], 0, v[140:141]
	s_add_i32 m0, s62, 0xe000
	s_nop 0
	global_load_lds_dwordx4 v[210:211], off
	s_waitcnt vmcnt(8)
	s_waitcnt lgkmcnt(0)
	s_barrier
	s_setprio 1
	s_waitcnt lgkmcnt(0)
	v_mfma_f32_16x16x32_bf16 v[126:129], v[146:149], v[178:181], v[126:129]
	v_mfma_f32_16x16x32_bf16 v[122:125], v[154:157], v[178:181], v[122:125]
	v_mfma_f32_16x16x32_bf16 v[110:113], v[146:149], v[186:189], v[110:113]
	v_mfma_f32_16x16x32_bf16 v[106:109], v[154:157], v[186:189], v[106:109]
	v_mfma_f32_16x16x32_bf16 v[94:97], v[146:149], v[194:197], v[94:97]
	v_mfma_f32_16x16x32_bf16 v[90:93], v[154:157], v[194:197], v[90:93]
	v_mfma_f32_16x16x32_bf16 v[78:81], v[146:149], v[202:205], v[78:81]
	v_mfma_f32_16x16x32_bf16 v[74:77], v[154:157], v[202:205], v[74:77]
	v_mfma_f32_16x16x32_bf16 v[126:129], v[150:153], v[182:185], v[126:129]
	v_mfma_f32_16x16x32_bf16 v[122:125], v[158:161], v[182:185], v[122:125]
	v_mfma_f32_16x16x32_bf16 v[110:113], v[150:153], v[190:193], v[110:113]
	v_mfma_f32_16x16x32_bf16 v[106:109], v[158:161], v[190:193], v[106:109]
	v_mfma_f32_16x16x32_bf16 v[94:97], v[150:153], v[198:201], v[94:97]
	v_mfma_f32_16x16x32_bf16 v[90:93], v[158:161], v[198:201], v[90:93]
	v_mfma_f32_16x16x32_bf16 v[78:81], v[150:153], v[206:209], v[78:81]
	v_mfma_f32_16x16x32_bf16 v[74:77], v[158:161], v[206:209], v[74:77]
	v_mfma_f32_16x16x32_bf16 v[118:121], v[162:165], v[178:181], v[118:121]
	v_mfma_f32_16x16x32_bf16 v[114:117], v[170:173], v[178:181], v[114:117]
	v_mfma_f32_16x16x32_bf16 v[102:105], v[162:165], v[186:189], v[102:105]
	v_mfma_f32_16x16x32_bf16 v[98:101], v[170:173], v[186:189], v[98:101]
	v_mfma_f32_16x16x32_bf16 v[86:89], v[162:165], v[194:197], v[86:89]
	v_mfma_f32_16x16x32_bf16 v[82:85], v[170:173], v[194:197], v[82:85]
	v_mfma_f32_16x16x32_bf16 v[70:73], v[162:165], v[202:205], v[70:73]
	v_mfma_f32_16x16x32_bf16 v[66:69], v[170:173], v[202:205], v[66:69]
	v_mfma_f32_16x16x32_bf16 v[118:121], v[166:169], v[182:185], v[118:121]
	v_mfma_f32_16x16x32_bf16 v[114:117], v[174:177], v[182:185], v[114:117]
	v_mfma_f32_16x16x32_bf16 v[102:105], v[166:169], v[190:193], v[102:105]
	v_mfma_f32_16x16x32_bf16 v[98:101], v[174:177], v[190:193], v[98:101]
	v_mfma_f32_16x16x32_bf16 v[86:89], v[166:169], v[198:201], v[86:89]
	v_mfma_f32_16x16x32_bf16 v[82:85], v[174:177], v[198:201], v[82:85]
	v_mfma_f32_16x16x32_bf16 v[70:73], v[166:169], v[206:209], v[70:73]
	v_mfma_f32_16x16x32_bf16 v[66:69], v[174:177], v[206:209], v[66:69]
	s_setprio 0
	s_barrier
	s_add_i32 s8, s10, s34
	v_lshl_add_u64 v[210:211], s[28:29], 0, v[130:131]
	s_mov_b32 m0, s8
	ds_read_b128 v[178:181], v145 offset:16384
	ds_read_b128 v[182:185], v145 offset:17408
	ds_read_b128 v[186:189], v145 offset:18432
	ds_read_b128 v[190:193], v145 offset:19456
	ds_read_b128 v[194:197], v145 offset:20480
	ds_read_b128 v[198:201], v145 offset:21504
	ds_read_b128 v[202:205], v145 offset:22528
	ds_read_b128 v[206:209], v145 offset:23552
	global_load_lds_dwordx4 v[210:211], off
	s_add_i32 m0, s8, 0x2000
	s_add_u32 s8, s28, 0x40000
	v_lshl_add_u64 v[212:213], s[28:29], 0, v[132:133]
	s_addc_u32 s9, s29, 0
	s_add_i32 s10, s11, s34
	global_load_lds_dwordx4 v[212:213], off
	v_lshl_add_u64 v[214:215], s[8:9], 0, v[130:131]
	s_mov_b32 m0, s10
	v_lshl_add_u64 v[216:217], s[40:41], 0, v[134:135]
	global_load_lds_dwordx4 v[214:215], off
	v_lshl_add_u64 v[214:215], s[8:9], 0, v[132:133]
	s_add_i32 m0, s10, 0x2000
	s_nop 0
	global_load_lds_dwordx4 v[214:215], off
	v_lshl_add_u64 v[214:215], s[40:41], 0, v[136:137]
	s_mov_b32 m0, s62
	s_nop 0
	global_load_lds_dwordx4 v[214:215], off
	s_mov_b32 m0, s63
	s_nop 0
	global_load_lds_dwordx4 v[216:217], off
	s_waitcnt vmcnt(8)
	s_waitcnt lgkmcnt(0)
	s_barrier
	s_setprio 1
	s_waitcnt lgkmcnt(0)
	v_mfma_f32_16x16x32_bf16 v[62:65], v[146:149], v[178:181], v[62:65]
	v_mfma_f32_16x16x32_bf16 v[58:61], v[154:157], v[178:181], v[58:61]
	v_mfma_f32_16x16x32_bf16 v[46:49], v[146:149], v[186:189], v[46:49]
	v_mfma_f32_16x16x32_bf16 v[42:45], v[154:157], v[186:189], v[42:45]
	v_mfma_f32_16x16x32_bf16 v[30:33], v[146:149], v[194:197], v[30:33]
	v_mfma_f32_16x16x32_bf16 v[26:29], v[154:157], v[194:197], v[26:29]
	v_mfma_f32_16x16x32_bf16 v[14:17], v[146:149], v[202:205], v[14:17]
	v_mfma_f32_16x16x32_bf16 v[10:13], v[154:157], v[202:205], v[10:13]
	v_mfma_f32_16x16x32_bf16 v[62:65], v[150:153], v[182:185], v[62:65]
	v_mfma_f32_16x16x32_bf16 v[58:61], v[158:161], v[182:185], v[58:61]
	v_mfma_f32_16x16x32_bf16 v[46:49], v[150:153], v[190:193], v[46:49]
	v_mfma_f32_16x16x32_bf16 v[42:45], v[158:161], v[190:193], v[42:45]
	v_mfma_f32_16x16x32_bf16 v[30:33], v[150:153], v[198:201], v[30:33]
	v_mfma_f32_16x16x32_bf16 v[26:29], v[158:161], v[198:201], v[26:29]
	v_mfma_f32_16x16x32_bf16 v[14:17], v[150:153], v[206:209], v[14:17]
	v_mfma_f32_16x16x32_bf16 v[10:13], v[158:161], v[206:209], v[10:13]
	v_mfma_f32_16x16x32_bf16 v[54:57], v[162:165], v[178:181], v[54:57]
	v_mfma_f32_16x16x32_bf16 v[50:53], v[170:173], v[178:181], v[50:53]
	v_mfma_f32_16x16x32_bf16 v[38:41], v[162:165], v[186:189], v[38:41]
	v_mfma_f32_16x16x32_bf16 v[34:37], v[170:173], v[186:189], v[34:37]
	v_mfma_f32_16x16x32_bf16 v[22:25], v[162:165], v[194:197], v[22:25]
	v_mfma_f32_16x16x32_bf16 v[18:21], v[170:173], v[194:197], v[18:21]
	v_mfma_f32_16x16x32_bf16 v[6:9], v[162:165], v[202:205], v[6:9]
	v_mfma_f32_16x16x32_bf16 v[2:5], v[170:173], v[202:205], v[2:5]
	v_mfma_f32_16x16x32_bf16 v[54:57], v[166:169], v[182:185], v[54:57]
	v_mfma_f32_16x16x32_bf16 v[50:53], v[174:177], v[182:185], v[50:53]
	v_mfma_f32_16x16x32_bf16 v[38:41], v[166:169], v[190:193], v[38:41]
	v_mfma_f32_16x16x32_bf16 v[34:37], v[174:177], v[190:193], v[34:37]
	v_mfma_f32_16x16x32_bf16 v[22:25], v[166:169], v[198:201], v[22:25]
	v_mfma_f32_16x16x32_bf16 v[18:21], v[174:177], v[198:201], v[18:21]
	v_mfma_f32_16x16x32_bf16 v[6:9], v[166:169], v[206:209], v[6:9]
	v_mfma_f32_16x16x32_bf16 v[2:5], v[174:177], v[206:209], v[2:5]
	s_setprio 0
	s_barrier
	s_add_i32 s10, 0, 0x18000
	s_add_i32 s11, 0, 0x1c000
	v_add_u32_e32 v158, s10, v1
	v_add_u32_e32 v174, s11, v1
	ds_read_b128 v[146:149], v158
	ds_read_b128 v[150:153], v158 offset:1024
	ds_read_b128 v[154:157], v158 offset:2048
	ds_read_b128 v[158:161], v158 offset:3072
	ds_read_b128 v[162:165], v174
	ds_read_b128 v[166:169], v174 offset:1024
	ds_read_b128 v[170:173], v174 offset:2048
	ds_read_b128 v[174:177], v174 offset:3072
	s_add_u32 s8, s40, 0x40000
	s_addc_u32 s9, s41, 0
	s_mov_b32 m0, s64
	v_lshl_add_u64 v[218:219], s[8:9], 0, v[136:137]
	ds_read_b128 v[178:181], v145 offset:32768
	ds_read_b128 v[182:185], v145 offset:33792
	ds_read_b128 v[186:189], v145 offset:34816
	ds_read_b128 v[190:193], v145 offset:35840
	ds_read_b128 v[194:197], v145 offset:36864
	ds_read_b128 v[198:201], v145 offset:37888
	ds_read_b128 v[202:205], v145 offset:38912
	ds_read_b128 v[206:209], v145 offset:39936
	global_load_lds_dwordx4 v[218:219], off
	v_lshl_add_u64 v[218:219], s[8:9], 0, v[134:135]
	s_mov_b32 m0, s65
	s_nop 0
	global_load_lds_dwordx4 v[218:219], off
	s_waitcnt vmcnt(8)
	s_waitcnt lgkmcnt(0)
	s_barrier
	s_setprio 1
	s_waitcnt lgkmcnt(0)
	v_mfma_f32_16x16x32_bf16 v[126:129], v[146:149], v[178:181], v[126:129]
	v_mfma_f32_16x16x32_bf16 v[122:125], v[154:157], v[178:181], v[122:125]
	v_mfma_f32_16x16x32_bf16 v[110:113], v[146:149], v[186:189], v[110:113]
	v_mfma_f32_16x16x32_bf16 v[106:109], v[154:157], v[186:189], v[106:109]
	v_mfma_f32_16x16x32_bf16 v[94:97], v[146:149], v[194:197], v[94:97]
	v_mfma_f32_16x16x32_bf16 v[90:93], v[154:157], v[194:197], v[90:93]
	v_mfma_f32_16x16x32_bf16 v[78:81], v[146:149], v[202:205], v[78:81]
	v_mfma_f32_16x16x32_bf16 v[74:77], v[154:157], v[202:205], v[74:77]
	v_mfma_f32_16x16x32_bf16 v[126:129], v[150:153], v[182:185], v[126:129]
	v_mfma_f32_16x16x32_bf16 v[122:125], v[158:161], v[182:185], v[122:125]
	v_mfma_f32_16x16x32_bf16 v[110:113], v[150:153], v[190:193], v[110:113]
	v_mfma_f32_16x16x32_bf16 v[106:109], v[158:161], v[190:193], v[106:109]
	v_mfma_f32_16x16x32_bf16 v[94:97], v[150:153], v[198:201], v[94:97]
	v_mfma_f32_16x16x32_bf16 v[90:93], v[158:161], v[198:201], v[90:93]
	v_mfma_f32_16x16x32_bf16 v[78:81], v[150:153], v[206:209], v[78:81]
	v_mfma_f32_16x16x32_bf16 v[74:77], v[158:161], v[206:209], v[74:77]
	v_mfma_f32_16x16x32_bf16 v[118:121], v[162:165], v[178:181], v[118:121]
	v_mfma_f32_16x16x32_bf16 v[114:117], v[170:173], v[178:181], v[114:117]
	v_mfma_f32_16x16x32_bf16 v[102:105], v[162:165], v[186:189], v[102:105]
	v_mfma_f32_16x16x32_bf16 v[98:101], v[170:173], v[186:189], v[98:101]
	v_mfma_f32_16x16x32_bf16 v[86:89], v[162:165], v[194:197], v[86:89]
	v_mfma_f32_16x16x32_bf16 v[82:85], v[170:173], v[194:197], v[82:85]
	v_mfma_f32_16x16x32_bf16 v[70:73], v[162:165], v[202:205], v[70:73]
	v_mfma_f32_16x16x32_bf16 v[66:69], v[170:173], v[202:205], v[66:69]
	v_mfma_f32_16x16x32_bf16 v[118:121], v[166:169], v[182:185], v[118:121]
	v_mfma_f32_16x16x32_bf16 v[114:117], v[174:177], v[182:185], v[114:117]
	v_mfma_f32_16x16x32_bf16 v[102:105], v[166:169], v[190:193], v[102:105]
	v_mfma_f32_16x16x32_bf16 v[98:101], v[174:177], v[190:193], v[98:101]
	v_mfma_f32_16x16x32_bf16 v[86:89], v[166:169], v[198:201], v[86:89]
	v_mfma_f32_16x16x32_bf16 v[82:85], v[174:177], v[198:201], v[82:85]
	v_mfma_f32_16x16x32_bf16 v[70:73], v[166:169], v[206:209], v[70:73]
	v_mfma_f32_16x16x32_bf16 v[66:69], v[174:177], v[206:209], v[66:69]
	s_setprio 0
	s_barrier
	s_add_i32 s8, s10, s34
	v_lshl_add_u64 v[210:211], v[210:211], 0, s[82:83]
	s_mov_b32 m0, s8
	ds_read_b128 v[178:181], v145 offset:49152
	ds_read_b128 v[182:185], v145 offset:50176
	ds_read_b128 v[186:189], v145 offset:51200
	ds_read_b128 v[190:193], v145 offset:52224
	ds_read_b128 v[194:197], v145 offset:53248
	ds_read_b128 v[198:201], v145 offset:54272
	ds_read_b128 v[202:205], v145 offset:55296
	ds_read_b128 v[206:209], v145 offset:56320
	global_load_lds_dwordx4 v[210:211], off
	s_add_i32 m0, s8, 0x2000
	s_add_u32 s8, s28, 0x40080
	v_lshl_add_u64 v[210:211], v[212:213], 0, s[82:83]
	s_addc_u32 s9, s29, 0
	s_add_i32 s10, s11, s34
	global_load_lds_dwordx4 v[210:211], off
	v_lshl_add_u64 v[210:211], s[8:9], 0, v[130:131]
	s_mov_b32 m0, s10
	s_nop 0
	global_load_lds_dwordx4 v[210:211], off
	v_lshl_add_u64 v[210:211], s[8:9], 0, v[132:133]
	s_add_i32 m0, s10, 0x2000
	s_nop 0
	global_load_lds_dwordx4 v[210:211], off
	v_lshl_add_u64 v[210:211], v[214:215], 0, s[82:83]
	s_mov_b32 m0, s66
	s_nop 0
	global_load_lds_dwordx4 v[210:211], off
	v_lshl_add_u64 v[210:211], v[216:217], 0, s[82:83]
	s_mov_b32 m0, s67
	s_nop 0
	global_load_lds_dwordx4 v[210:211], off
	s_waitcnt vmcnt(8)
	s_waitcnt lgkmcnt(0)
	s_barrier
	s_setprio 1
	s_waitcnt lgkmcnt(0)
	v_mfma_f32_16x16x32_bf16 v[62:65], v[146:149], v[178:181], v[62:65]
	v_mfma_f32_16x16x32_bf16 v[58:61], v[154:157], v[178:181], v[58:61]
	v_mfma_f32_16x16x32_bf16 v[46:49], v[146:149], v[186:189], v[46:49]
	v_mfma_f32_16x16x32_bf16 v[42:45], v[154:157], v[186:189], v[42:45]
	v_mfma_f32_16x16x32_bf16 v[30:33], v[146:149], v[194:197], v[30:33]
	v_mfma_f32_16x16x32_bf16 v[26:29], v[154:157], v[194:197], v[26:29]
	v_mfma_f32_16x16x32_bf16 v[14:17], v[146:149], v[202:205], v[14:17]
	v_mfma_f32_16x16x32_bf16 v[10:13], v[154:157], v[202:205], v[10:13]
	v_mfma_f32_16x16x32_bf16 v[62:65], v[150:153], v[182:185], v[62:65]
	v_mfma_f32_16x16x32_bf16 v[58:61], v[158:161], v[182:185], v[58:61]
	v_mfma_f32_16x16x32_bf16 v[46:49], v[150:153], v[190:193], v[46:49]
	v_mfma_f32_16x16x32_bf16 v[42:45], v[158:161], v[190:193], v[42:45]
	v_mfma_f32_16x16x32_bf16 v[30:33], v[150:153], v[198:201], v[30:33]
	v_mfma_f32_16x16x32_bf16 v[26:29], v[158:161], v[198:201], v[26:29]
	v_mfma_f32_16x16x32_bf16 v[14:17], v[150:153], v[206:209], v[14:17]
	v_mfma_f32_16x16x32_bf16 v[10:13], v[158:161], v[206:209], v[10:13]
	v_mfma_f32_16x16x32_bf16 v[54:57], v[162:165], v[178:181], v[54:57]
	v_mfma_f32_16x16x32_bf16 v[50:53], v[170:173], v[178:181], v[50:53]
	v_mfma_f32_16x16x32_bf16 v[38:41], v[162:165], v[186:189], v[38:41]
	v_mfma_f32_16x16x32_bf16 v[34:37], v[170:173], v[186:189], v[34:37]
	v_mfma_f32_16x16x32_bf16 v[22:25], v[162:165], v[194:197], v[22:25]
	v_mfma_f32_16x16x32_bf16 v[18:21], v[170:173], v[194:197], v[18:21]
	v_mfma_f32_16x16x32_bf16 v[6:9], v[162:165], v[202:205], v[6:9]
	v_mfma_f32_16x16x32_bf16 v[2:5], v[170:173], v[202:205], v[2:5]
	v_mfma_f32_16x16x32_bf16 v[54:57], v[166:169], v[182:185], v[54:57]
	v_mfma_f32_16x16x32_bf16 v[50:53], v[174:177], v[182:185], v[50:53]
	v_mfma_f32_16x16x32_bf16 v[38:41], v[166:169], v[190:193], v[38:41]
	v_mfma_f32_16x16x32_bf16 v[34:37], v[174:177], v[190:193], v[34:37]
	v_mfma_f32_16x16x32_bf16 v[22:25], v[166:169], v[198:201], v[22:25]
	v_mfma_f32_16x16x32_bf16 v[18:21], v[174:177], v[198:201], v[18:21]
	v_mfma_f32_16x16x32_bf16 v[6:9], v[166:169], v[206:209], v[6:9]
	v_mfma_f32_16x16x32_bf16 v[2:5], v[174:177], v[206:209], v[2:5]
	s_setprio 0
	s_barrier
	s_add_i32 s84, s84, 2
	s_add_u32 s60, s60, 0x100
	s_addc_u32 s61, s61, 0
	s_add_u32 s76, s76, 0x100
	s_addc_u32 s77, s77, 0
	s_cmp_gt_u32 s84, 13
	s_cbranch_scc0 .LBB0_497
	s_and_b64 vcc, exec, s[50:51]
	s_cbranch_vccz .LBB0_500
	s_barrier
